# GEMM1: hand-written straight-line fast epilogue path for u=C*v tiles (type<8), ~95 instr instead of ~320 through generic dispatch
# baseline (speedup 1.0000x reference)
; __device__ __forceinline__ u32x4 pk8(f32x4 a, f32x4 b) { u32x4 w; w.x = pk2(a[0], a[1]); w.y = pk2(a[2], a[3]); w.z = pk2(b[0], b[1]); w.w = pk2(b[2], b[3]); return w; }
;     __device__ __forceinline__ void operator()(const AccT& acc, const Unit& u, int wr, int wc, int fr_, int fq_) const {
;     ...
;         const int pn = u.pn < 8 ? u.pn : u.pn + 8, cb = wc * 32 + 8 * fq;
;         bf16_t* const U = (bf16_t*)(ws + WS_RB); bf16_t* const A2 = (bf16_t*)(ws + WS_A2); bf16_t* const QL = (bf16_t*)(ws + WS_QL); bf16_t* const KVL = (bf16_t*)(ws + WS_KVL); bf16_t* const KPE = (bf16_t*)(ws + WS_KPE);
;         bf16_t* const R = (bf16_t*)out; bf16_t* const SB = (bf16_t*)out + (size_t)T * 1024; float* const ssq_q = (float*)(ws + WS_SSQ); float* const ssq_kv = ssq_q + T; const float* const rope = (const float*)(ws + WS_ROPE);
; #pragma unroll
;         for (int ai = 0; ai < 2; ++ai)
; #pragma unroll
;             for (int m = 0; m < 4; ++m) {
;                 const size_t row = (size_t)ROW_OF(ai, m);
;                 const f32x4 a0 = acc[ai][0][m][0], a1 = acc[ai][0][m][1], b0 = acc[ai][1][m][0], b1 = acc[ai][1][m][1];
;                 if (pn < 8) {
;                     st16c(U + row * 1024 + pn * 128 + cb, pk8(a0 * b0, a1 * b1));
.LBB0_359:
	s_add_i32 s4, s10, 8
	s_cmp_lt_i32 s10, 8
	s_cselect_b32 s82, s10, s4
	s_cmp_lg_u32 s82, 18
	s_cselect_b32 s99, 1, 0
	s_cmp_lt_u32 s82, 8
	s_cbranch_scc1 .Lg1u_fast
	s_cmp_gt_i32 s82, 7
	s_cselect_b64 s[10:11], -1, 0
	s_cmp_gt_u32 s82, 22
	s_cselect_b64 s[48:49], -1, 0
	s_lshl_b32 s6, s82, 7
	s_add_i32 s16, s6, 0xfffff480
	s_lshl_b64 s[46:47], s[16:17], 1
	v_mov_b32_e32 v136, v201
	v_mov_b32_e32 v150, v232
	s_add_u32 s50, s88, s46
	s_addc_u32 s51, s89, s47
	v_lshl_add_u32 v148, v150, 3, s67
	v_lshlrev_b32_e32 v146, 4, v150
	v_ashrrev_i32_e32 v149, 31, v148
	s_add_u32 s46, s71, s46
	v_ashrrev_i32_e32 v147, 31, v146
	v_lshlrev_b64 v[160:161], 1, v[148:149]
	s_addc_u32 s47, s72, s47
	s_lshl_b32 s7, s82, 9
	v_lshl_add_u64 v[158:159], v[146:147], 2, s[36:37]
	v_lshlrev_b32_e32 v146, 8, v150
	v_cmp_eq_u32_e64 s[4:5], 0, v150
	v_lshl_add_u64 v[150:151], s[46:47], 0, v[160:161]
	s_add_u32 s46, s90, s7
	s_addc_u32 s47, s91, 0
	s_ashr_i32 s7, s6, 31
	s_lshl_b64 s[6:7], s[6:7], 1
	s_add_u32 s6, s69, s6
	s_addc_u32 s7, s70, s7
	s_lshl_b32 s16, s33, 8
	s_add_i32 s16, s16, s66
	v_and_b32_e32 v175, 0x100, v146
	v_and_b32_e32 v156, 0xfffffe00, v146
	v_add_u32_e32 v146, s16, v136
	v_ashrrev_i32_e32 v157, 31, v156
	v_lshl_add_u64 v[154:155], s[28:29], 0, v[160:161]
	v_lshl_add_u64 v[152:153], s[50:51], 0, v[160:161]
	v_ashrrev_i32_e32 v147, 31, v146
	s_mov_b64 s[50:51], -1
	s_and_b64 vcc, exec, s[10:11]
	s_cbranch_vccz .LBB0_391
	s_cmp_gt_u32 s82, 18
	s_cbranch_scc1 .LBB0_382
	s_mov_b64 s[54:55], -1
	s_mov_b64 s[50:51], 0
	s_cmp_lt_i32 s82, 17
	s_mov_b64 s[52:53], 0
	s_cbranch_scc0 .LBB0_364
	s_and_b64 vcc, exec, s[54:55]
	s_cbranch_vccnz .LBB0_381

; __device__ __forceinline__ u32x4 pk8(f32x4 a, f32x4 b) { u32x4 w; w.x = pk2(a[0], a[1]); w.y = pk2(a[2], a[3]); w.z = pk2(b[0], b[1]); w.w = pk2(b[2], b[3]); return w; }
;     __device__ __forceinline__ void operator()(const AccT& acc, const Unit& u, int wr, int wc, int fr_, int fq_) const {
;     ...
;                 const size_t row = (size_t)ROW_OF(ai, m);
;                 const f32x4 a0 = acc[ai][0][m][0], a1 = acc[ai][0][m][1], b0 = acc[ai][1][m][0], b1 = acc[ai][1][m][1];
;                 if (pn < 8) {
;                     st16c(U + row * 1024 + pn * 128 + cb, pk8(a0 * b0, a1 * b1));
.Lg1u_fast:
	s_lshl_b32 s16, s33, 8
	s_add_i32 s16, s16, s66
	v_add_u32_e32 v146, s16, v201
	v_lshl_add_u32 v148, v232, 3, s67
	s_lshl_b32 s6, s82, 8
	s_add_u32 s6, s69, s6
	s_addc_u32 s7, s70, 0
	v_lshlrev_b32_e32 v160, 1, v148
	v_mov_b32_e32 v161, 0
	v_lshlrev_b32_e32 v162, 11, v146
	v_mov_b32_e32 v163, 0
	v_lshl_add_u64 v[160:161], v[160:161], 0, v[162:163]
	v_lshl_add_u64 v[160:161], s[6:7], 0, v[160:161]
	s_mov_b64 s[50:51], 0x8000
	s_mov_b64 s[4:5], 0x28000
	v_pk_mul_f32 v[122:123], v[126:127], v[122:123]
	v_pk_mul_f32 v[120:121], v[124:125], v[120:121]
	v_pk_mul_f32 v[118:119], v[114:115], v[118:119]
	v_pk_mul_f32 v[114:115], v[112:113], v[116:117]
	v_cvt_pk_bf16_f32 v112, v120, v121
	v_cvt_pk_bf16_f32 v113, v122, v123
	v_cvt_pk_bf16_f32 v114, v114, v115
	v_cvt_pk_bf16_f32 v115, v118, v119
	global_store_dwordx4 v[160:161], v[112:115], off
	v_pk_mul_f32 v[106:107], v[106:107], v[110:111]
	v_pk_mul_f32 v[104:105], v[104:105], v[108:109]
	v_pk_mul_f32 v[102:103], v[98:99], v[102:103]
	v_pk_mul_f32 v[98:99], v[96:97], v[100:101]
	v_lshl_add_u64 v[160:161], v[160:161], 0, s[50:51]
	v_cvt_pk_bf16_f32 v96, v104, v105
	v_cvt_pk_bf16_f32 v97, v106, v107
	v_cvt_pk_bf16_f32 v98, v98, v99
	v_cvt_pk_bf16_f32 v99, v102, v103
	global_store_dwordx4 v[160:161], v[96:99], off
	v_pk_mul_f32 v[90:91], v[90:91], v[94:95]
	v_pk_mul_f32 v[88:89], v[88:89], v[92:93]
	v_pk_mul_f32 v[86:87], v[82:83], v[86:87]
	v_pk_mul_f32 v[82:83], v[80:81], v[84:85]
	v_lshl_add_u64 v[160:161], v[160:161], 0, s[50:51]
	v_cvt_pk_bf16_f32 v80, v88, v89
	v_cvt_pk_bf16_f32 v81, v90, v91
	v_cvt_pk_bf16_f32 v82, v82, v83
	v_cvt_pk_bf16_f32 v83, v86, v87
	global_store_dwordx4 v[160:161], v[80:83], off
	v_pk_mul_f32 v[74:75], v[74:75], v[78:79]
	v_pk_mul_f32 v[72:73], v[72:73], v[76:77]
	v_pk_mul_f32 v[70:71], v[66:67], v[70:71]
	v_pk_mul_f32 v[66:67], v[64:65], v[68:69]
	v_lshl_add_u64 v[160:161], v[160:161], 0, s[50:51]
	v_cvt_pk_bf16_f32 v64, v72, v73
	v_cvt_pk_bf16_f32 v65, v74, v75
	v_cvt_pk_bf16_f32 v66, v66, v67
	v_cvt_pk_bf16_f32 v67, v70, v71
	global_store_dwordx4 v[160:161], v[64:67], off
	v_pk_mul_f32 v[58:59], v[58:59], v[62:63]
	v_pk_mul_f32 v[56:57], v[56:57], v[60:61]
	v_pk_mul_f32 v[54:55], v[50:51], v[54:55]
	v_pk_mul_f32 v[50:51], v[48:49], v[52:53]
	v_lshl_add_u64 v[160:161], v[160:161], 0, s[4:5]
	v_cvt_pk_bf16_f32 v48, v56, v57
	v_cvt_pk_bf16_f32 v49, v58, v59
	v_cvt_pk_bf16_f32 v50, v50, v51
	v_cvt_pk_bf16_f32 v51, v54, v55
	global_store_dwordx4 v[160:161], v[48:51], off
	v_pk_mul_f32 v[42:43], v[42:43], v[46:47]
	v_pk_mul_f32 v[40:41], v[40:41], v[44:45]
	v_pk_mul_f32 v[38:39], v[34:35], v[38:39]
	v_pk_mul_f32 v[34:35], v[32:33], v[36:37]
	v_lshl_add_u64 v[160:161], v[160:161], 0, s[50:51]
	v_cvt_pk_bf16_f32 v32, v40, v41
	v_cvt_pk_bf16_f32 v33, v42, v43
	v_cvt_pk_bf16_f32 v34, v34, v35
	v_cvt_pk_bf16_f32 v35, v38, v39
	global_store_dwordx4 v[160:161], v[32:35], off
	v_pk_mul_f32 v[26:27], v[26:27], v[30:31]
	v_pk_mul_f32 v[24:25], v[24:25], v[28:29]
	v_pk_mul_f32 v[22:23], v[18:19], v[22:23]
	v_pk_mul_f32 v[18:19], v[16:17], v[20:21]
	v_lshl_add_u64 v[160:161], v[160:161], 0, s[50:51]
	v_cvt_pk_bf16_f32 v16, v24, v25
	v_cvt_pk_bf16_f32 v17, v26, v27
	v_cvt_pk_bf16_f32 v18, v18, v19
	v_cvt_pk_bf16_f32 v19, v22, v23
	global_store_dwordx4 v[160:161], v[16:19], off
	v_pk_mul_f32 v[10:11], v[10:11], v[14:15]
	v_pk_mul_f32 v[8:9], v[8:9], v[12:13]
	v_pk_mul_f32 v[6:7], v[2:3], v[6:7]
	v_pk_mul_f32 v[2:3], v[0:1], v[4:5]
	v_lshl_add_u64 v[160:161], v[160:161], 0, s[50:51]
	v_cvt_pk_bf16_f32 v0, v8, v9
	v_cvt_pk_bf16_f32 v1, v10, v11
	v_cvt_pk_bf16_f32 v2, v2, v3
	v_cvt_pk_bf16_f32 v3, v6, v7
	global_store_dwordx4 v[160:161], v[0:3], off
	s_branch .LBB0_599
